# v42 plus: GEMM accumulator zeroing at unit start uses 64-bit moves (64 instead of 128 VALU)
# speedup vs baseline: 1.0113x; 1.0014x over previous
;   DI bool next(int k, Unit& u) const {
;     const int g = blockIdx.x & 7, j = blockIdx.x >> 3, J = gridDim.x >> 3;
;     const int q = k * J + j;
;     if (q >= R * NT) return false;
; template <class Epi>
; DI void gemm_phase(LAS unsigned char* lds, const u16* __restrict__ Aptr, int lda, const u16* __restrict__ Btptr, int K, const Order& S, const Epi& E) {
;     ...
;     const bool has_next = S.next(ui + 1, nxt);
;     const char* nA = has_next ? (const char*)Aptr + (size_t)nxt.pm * tstepA : cA;
;     const char* nB = has_next ? (const char*)Btptr + (size_t)nxt.pn * tstepB : cB;
;     for (int t = 0; t < nt; t += 2) {
;       const bool last = (t == nt - 2);
;       const char* a1 = cA + (size_t)(t + 1) * kstep;
;       const char* a2 = last ? nA : cA + (size_t)(t + 2) * kstep;
;       const char* b2 = last ? nB : cB + (size_t)(t + 2) * kstep;
;       const char* a3 = a2 + kstep;
;       const char* b3 = b2 + kstep;
;       G8_LDB(B0, 0, 0); G8_SCHED; G8_LDA(At, 0, 0); G8_STAGE(G8_SA(1, 1), a1 + hstepA, voffA);
;       G8_WAIT_L(8); G8_BAR; G8_WAIT_L(0); G8_MMA(0, 0, At, B0); G8_BAR; G8_SCHED;
;       G8_LDB(B1, 0, 1); G8_STAGE(G8_SB(0, 0), b2, voffB);
;       G8_BAR; G8_WAIT_L(0); G8_MMA(0, 1, At, B1); G8_BAR;
;       G8_LDA(At, 0, 1); G8_STAGE(G8_SA(0, 0), a2, voffA);
;       G8_BAR; G8_WAIT_L(0); G8_MMA(1, 0, At, B0); G8_BAR; G8_SCHED;
;       G8_STAGE(G8_SB(0, 1), b2 + hstepB, voffB);
;       G8_WAIT_V(6); G8_BAR; G8_MMA(1, 1, At, B1); G8_BAR;
;       G8_LDB(B0, 1, 0); G8_SCHED; G8_LDA(At, 1, 0); G8_STAGE(G8_SA(0, 1), a2 + hstepA, voffA);
;       G8_WAIT_L(8); G8_BAR; G8_WAIT_L(0); G8_MMA(0, 0, At, B0); G8_BAR; G8_SCHED;
;       G8_LDB(B1, 1, 1); G8_STAGE(G8_SB(1, 0), b3, voffB);
;       G8_BAR; G8_WAIT_L(0); G8_MMA(0, 1, At, B1); G8_BAR;
;       G8_LDA(At, 1, 1); G8_STAGE(G8_SA(1, 0), a3, voffA);
;       G8_BAR; G8_WAIT_L(0); G8_MMA(1, 0, At, B0); G8_BAR; G8_SCHED;
;       G8_STAGE(G8_SB(1, 1), b3 + hstepB, voffB);
;       G8_WAIT_V(6); G8_BAR; G8_MMA(1, 1, At, B1); G8_BAR;
;     }
;     E(acc, cur, wr, wc, fr, fq);
;     if (!has_next) break;
; #pragma unroll
;     for (int a = 0; a < 2; ++a)
; #pragma unroll
;       for (int b = 0; b < 2; ++b)
; #pragma unroll
;         for (int m = 0; m < 4; ++m)
; #pragma unroll
;           for (int n = 0; n < 2; ++n) acc[a][b][m][n] = (f32x4v){0.f, 0.f, 0.f, 0.f};
;     cur = nxt; cA = nA; cB = nB; ++ui;
.LBB0_166:
	s_ashr_i32 s27, s26, 31
	s_lshl_b64 s[34:35], s[26:27], 17
	s_add_u32 s34, s8, s34
	s_addc_u32 s35, s9, s35
	s_and_b64 s[38:39], s[38:39], exec
	v_mov_b32_e32 v0, 0
	s_cselect_b32 s27, s35, s37
	s_cselect_b32 s58, s34, s36
	s_mov_b32 s42, 0
	s_mov_b64 s[38:39], -1
	s_mov_b64 s[40:41], 0
	v_mov_b32_e32 v1, v0
	v_mov_b64_e32 v[2:3], v[0:1]
	v_mov_b64_e32 v[4:5], v[0:1]
	v_mov_b64_e32 v[6:7], v[0:1]
	v_mov_b64_e32 v[8:9], v[0:1]
	v_mov_b64_e32 v[10:11], v[0:1]
	v_mov_b64_e32 v[12:13], v[0:1]
	v_mov_b64_e32 v[14:15], v[0:1]
	v_mov_b64_e32 v[16:17], v[0:1]
	v_mov_b64_e32 v[18:19], v[0:1]
	v_mov_b64_e32 v[20:21], v[0:1]
	v_mov_b64_e32 v[22:23], v[0:1]
	v_mov_b64_e32 v[24:25], v[0:1]
	v_mov_b64_e32 v[26:27], v[0:1]
	v_mov_b64_e32 v[28:29], v[0:1]
	v_mov_b64_e32 v[30:31], v[0:1]
	v_mov_b64_e32 v[32:33], v[0:1]
	v_mov_b64_e32 v[34:35], v[0:1]
	v_mov_b64_e32 v[36:37], v[0:1]
	v_mov_b64_e32 v[38:39], v[0:1]
	v_mov_b64_e32 v[40:41], v[0:1]
	v_mov_b64_e32 v[42:43], v[0:1]
	v_mov_b64_e32 v[44:45], v[0:1]
	v_mov_b64_e32 v[46:47], v[0:1]
	v_mov_b64_e32 v[48:49], v[0:1]
	v_mov_b64_e32 v[50:51], v[0:1]
	v_mov_b64_e32 v[52:53], v[0:1]
	v_mov_b64_e32 v[54:55], v[0:1]
	v_mov_b64_e32 v[56:57], v[0:1]
	v_mov_b64_e32 v[58:59], v[0:1]
	v_mov_b64_e32 v[60:61], v[0:1]
	v_mov_b64_e32 v[62:63], v[0:1]
	v_mov_b64_e32 v[64:65], v[0:1]
	v_mov_b64_e32 v[66:67], v[0:1]
	v_mov_b64_e32 v[68:69], v[0:1]
	v_mov_b64_e32 v[70:71], v[0:1]
	v_mov_b64_e32 v[72:73], v[0:1]
	v_mov_b64_e32 v[74:75], v[0:1]
	v_mov_b64_e32 v[76:77], v[0:1]
	v_mov_b64_e32 v[78:79], v[0:1]
	v_mov_b64_e32 v[80:81], v[0:1]
	v_mov_b64_e32 v[82:83], v[0:1]
	v_mov_b64_e32 v[84:85], v[0:1]
	v_mov_b64_e32 v[86:87], v[0:1]
	v_mov_b64_e32 v[88:89], v[0:1]
	v_mov_b64_e32 v[90:91], v[0:1]
	v_mov_b64_e32 v[92:93], v[0:1]
	v_mov_b64_e32 v[94:95], v[0:1]
	v_mov_b64_e32 v[96:97], v[0:1]
	v_mov_b64_e32 v[98:99], v[0:1]
	v_mov_b64_e32 v[100:101], v[0:1]
	v_mov_b64_e32 v[102:103], v[0:1]
	v_mov_b64_e32 v[104:105], v[0:1]
	v_mov_b64_e32 v[106:107], v[0:1]
	v_mov_b64_e32 v[108:109], v[0:1]
	v_mov_b64_e32 v[110:111], v[0:1]
	v_mov_b64_e32 v[112:113], v[0:1]
	v_mov_b64_e32 v[114:115], v[0:1]
	v_mov_b64_e32 v[116:117], v[0:1]
	v_mov_b64_e32 v[118:119], v[0:1]
	v_mov_b64_e32 v[120:121], v[0:1]
	v_mov_b64_e32 v[122:123], v[0:1]
	v_mov_b64_e32 v[124:125], v[0:1]
	v_mov_b64_e32 v[126:127], v[0:1]

; template <class Epi>
; DI void gemm_phase(LAS unsigned char* lds, const u16* __restrict__ Aptr, int lda, const u16* __restrict__ Btptr, int K, const Order& S, const Epi& E) {
;     ...
;     const bool has_next = S.next(ui + 1, nxt);
;     const char* nA = has_next ? (const char*)Aptr + (size_t)nxt.pm * tstepA : cA;
;     const char* nB = has_next ? (const char*)Btptr + (size_t)nxt.pn * tstepB : cB;
;     for (int t = 0; t < nt; t += 2) {
;       const bool last = (t == nt - 2);
;       const char* a1 = cA + (size_t)(t + 1) * kstep;
;       const char* a2 = last ? nA : cA + (size_t)(t + 2) * kstep;
;       const char* b2 = last ? nB : cB + (size_t)(t + 2) * kstep;
;       const char* a3 = a2 + kstep;
;       const char* b3 = b2 + kstep;
;       G8_LDB(B0, 0, 0); G8_SCHED; G8_LDA(At, 0, 0); G8_STAGE(G8_SA(1, 1), a1 + hstepA, voffA);
;       G8_WAIT_L(8); G8_BAR; G8_WAIT_L(0); G8_MMA(0, 0, At, B0); G8_BAR; G8_SCHED;
;       G8_LDB(B1, 0, 1); G8_STAGE(G8_SB(0, 0), b2, voffB);
;       G8_BAR; G8_WAIT_L(0); G8_MMA(0, 1, At, B1); G8_BAR;
;       G8_LDA(At, 0, 1); G8_STAGE(G8_SA(0, 0), a2, voffA);
;       G8_BAR; G8_WAIT_L(0); G8_MMA(1, 0, At, B0); G8_BAR; G8_SCHED;
;       G8_STAGE(G8_SB(0, 1), b2 + hstepB, voffB);
;       G8_WAIT_V(6); G8_BAR; G8_MMA(1, 1, At, B1); G8_BAR;
;       G8_LDB(B0, 1, 0); G8_SCHED; G8_LDA(At, 1, 0); G8_STAGE(G8_SA(0, 1), a2 + hstepA, voffA);
;       G8_WAIT_L(8); G8_BAR; G8_WAIT_L(0); G8_MMA(0, 0, At, B0); G8_BAR; G8_SCHED;
;       G8_LDB(B1, 1, 1); G8_STAGE(G8_SB(1, 0), b3, voffB);
;       G8_BAR; G8_WAIT_L(0); G8_MMA(0, 1, At, B1); G8_BAR;
;       G8_LDA(At, 1, 1); G8_STAGE(G8_SA(1, 0), a3, voffA);
;       G8_BAR; G8_WAIT_L(0); G8_MMA(1, 0, At, B0); G8_BAR; G8_SCHED;
;       G8_STAGE(G8_SB(1, 1), b3 + hstepB, voffB);
;       G8_WAIT_V(6); G8_BAR; G8_MMA(1, 1, At, B1); G8_BAR;
;     }
;     E(acc, cur, wr, wc, fr, fq);
;     if (!has_next) break;
; #pragma unroll
;     for (int a = 0; a < 2; ++a)
; #pragma unroll
;       for (int b = 0; b < 2; ++b)
; #pragma unroll
;         for (int m = 0; m < 4; ++m)
; #pragma unroll
;           for (int n = 0; n < 2; ++n) acc[a][b][m][n] = (f32x4v){0.f, 0.f, 0.f, 0.f};
;     cur = nxt; cA = nA; cB = nB; ++ui;
;   DI void operator()(const f32x4v (&acc)[2][2][4][2], const Unit& u, int wr, int wc, int fr, int fq) const {
;     ...
;     float rsv[2][4];
; #pragma unroll
;     for (int ai = 0; ai < 2; ++ai)
.LBB0_227:
	s_ashr_i32 s37, s36, 31
	s_lshl_b64 s[34:35], s[36:37], 19
	s_add_u32 s34, s24, s34
	s_addc_u32 s35, s25, s35
	s_and_b64 s[56:57], s[74:75], exec
	s_cselect_b32 s37, s35, s3
	s_cselect_b32 s56, s34, s2
	s_ashr_i32 s39, s38, 31
	s_lshl_b64 s[58:59], s[38:39], 19
	s_add_u32 s96, s88, s58
	s_addc_u32 s97, s93, s59
	s_and_b64 s[58:59], s[74:75], exec
	s_cselect_b32 s39, s97, s73
	s_cselect_b32 s57, s96, s72
	s_add_u32 s2, s2, 0x40080
	s_addc_u32 s3, s3, 0
	s_add_u32 s58, s72, 0x100
	v_mov_b32_e32 v0, 0
	s_addc_u32 s59, s73, 0
	s_mov_b32 s60, -2
	v_mov_b32_e32 v1, v0
	v_mov_b64_e32 v[2:3], v[0:1]
	v_mov_b64_e32 v[4:5], v[0:1]
	v_mov_b64_e32 v[6:7], v[0:1]
	v_mov_b64_e32 v[8:9], v[0:1]
	v_mov_b64_e32 v[10:11], v[0:1]
	v_mov_b64_e32 v[12:13], v[0:1]
	v_mov_b64_e32 v[14:15], v[0:1]
	v_mov_b64_e32 v[16:17], v[0:1]
	v_mov_b64_e32 v[18:19], v[0:1]
	v_mov_b64_e32 v[20:21], v[0:1]
	v_mov_b64_e32 v[22:23], v[0:1]
	v_mov_b64_e32 v[24:25], v[0:1]
	v_mov_b64_e32 v[26:27], v[0:1]
	v_mov_b64_e32 v[28:29], v[0:1]
	v_mov_b64_e32 v[30:31], v[0:1]
	v_mov_b64_e32 v[32:33], v[0:1]
	v_mov_b64_e32 v[34:35], v[0:1]
	v_mov_b64_e32 v[36:37], v[0:1]
	v_mov_b64_e32 v[38:39], v[0:1]
	v_mov_b64_e32 v[40:41], v[0:1]
	v_mov_b64_e32 v[42:43], v[0:1]
	v_mov_b64_e32 v[44:45], v[0:1]
	v_mov_b64_e32 v[46:47], v[0:1]
	v_mov_b64_e32 v[48:49], v[0:1]
	v_mov_b64_e32 v[50:51], v[0:1]
	v_mov_b64_e32 v[52:53], v[0:1]
	v_mov_b64_e32 v[54:55], v[0:1]
	v_mov_b64_e32 v[56:57], v[0:1]
	v_mov_b64_e32 v[58:59], v[0:1]
	v_mov_b64_e32 v[60:61], v[0:1]
	v_mov_b64_e32 v[62:63], v[0:1]
	v_mov_b64_e32 v[64:65], v[0:1]
	v_mov_b64_e32 v[66:67], v[0:1]
	v_mov_b64_e32 v[68:69], v[0:1]
	v_mov_b64_e32 v[70:71], v[0:1]
	v_mov_b64_e32 v[72:73], v[0:1]
	v_mov_b64_e32 v[74:75], v[0:1]
	v_mov_b64_e32 v[76:77], v[0:1]
	v_mov_b64_e32 v[78:79], v[0:1]
	v_mov_b64_e32 v[80:81], v[0:1]
	v_mov_b64_e32 v[82:83], v[0:1]
	v_mov_b64_e32 v[84:85], v[0:1]
	v_mov_b64_e32 v[86:87], v[0:1]
	v_mov_b64_e32 v[88:89], v[0:1]
	v_mov_b64_e32 v[90:91], v[0:1]
	v_mov_b64_e32 v[92:93], v[0:1]
	v_mov_b64_e32 v[94:95], v[0:1]
	v_mov_b64_e32 v[96:97], v[0:1]
	v_mov_b64_e32 v[98:99], v[0:1]
	v_mov_b64_e32 v[100:101], v[0:1]
	v_mov_b64_e32 v[102:103], v[0:1]
	v_mov_b64_e32 v[104:105], v[0:1]
	v_mov_b64_e32 v[106:107], v[0:1]
	v_mov_b64_e32 v[108:109], v[0:1]
	v_mov_b64_e32 v[110:111], v[0:1]
	v_mov_b64_e32 v[112:113], v[0:1]
	v_mov_b64_e32 v[114:115], v[0:1]
	v_mov_b64_e32 v[116:117], v[0:1]
	v_mov_b64_e32 v[118:119], v[0:1]
	v_mov_b64_e32 v[120:121], v[0:1]
	v_mov_b64_e32 v[122:123], v[0:1]
	v_mov_b64_e32 v[124:125], v[0:1]
	v_mov_b64_e32 v[126:127], v[0:1]
	v_lshl_add_u32 v214, s64, 8, v138
	v_ashrrev_i32_e32 v215, 31, v214
	v_lshl_add_u64 v[214:215], v[214:215], 2, s[16:17]
	global_load_dword v238, v[214:215], off
	global_load_dword v239, v[214:215], off offset:64
	global_load_dword v240, v[214:215], off offset:128
	global_load_dword v241, v[214:215], off offset:192
	global_load_dword v242, v[214:215], off offset:512
	global_load_dword v243, v[214:215], off offset:576
	global_load_dword v216, v[214:215], off offset:640
	global_load_dword v217, v[214:215], off offset:704

;   DI bool next(int k, Unit& u) const {
;     const int g = blockIdx.x & 7, j = blockIdx.x >> 3, J = gridDim.x >> 3;
;     const int q = k * J + j;
;     if (q >= R * NT) return false;
; template <class Epi>
; DI void gemm_phase(LAS unsigned char* lds, const u16* __restrict__ Aptr, int lda, const u16* __restrict__ Btptr, int K, const Order& S, const Epi& E) {
;     ...
;     const bool has_next = S.next(ui + 1, nxt);
;     const char* nA = has_next ? (const char*)Aptr + (size_t)nxt.pm * tstepA : cA;
;     const char* nB = has_next ? (const char*)Btptr + (size_t)nxt.pn * tstepB : cB;
;     for (int t = 0; t < nt; t += 2) {
;       const bool last = (t == nt - 2);
;       const char* a1 = cA + (size_t)(t + 1) * kstep;
;       const char* a2 = last ? nA : cA + (size_t)(t + 2) * kstep;
;       const char* b2 = last ? nB : cB + (size_t)(t + 2) * kstep;
;       const char* a3 = a2 + kstep;
;       const char* b3 = b2 + kstep;
;       G8_LDB(B0, 0, 0); G8_SCHED; G8_LDA(At, 0, 0); G8_STAGE(G8_SA(1, 1), a1 + hstepA, voffA);
;       G8_WAIT_L(8); G8_BAR; G8_WAIT_L(0); G8_MMA(0, 0, At, B0); G8_BAR; G8_SCHED;
;       G8_LDB(B1, 0, 1); G8_STAGE(G8_SB(0, 0), b2, voffB);
;       G8_BAR; G8_WAIT_L(0); G8_MMA(0, 1, At, B1); G8_BAR;
;       G8_LDA(At, 0, 1); G8_STAGE(G8_SA(0, 0), a2, voffA);
;       G8_BAR; G8_WAIT_L(0); G8_MMA(1, 0, At, B0); G8_BAR; G8_SCHED;
;       G8_STAGE(G8_SB(0, 1), b2 + hstepB, voffB);
;       G8_WAIT_V(6); G8_BAR; G8_MMA(1, 1, At, B1); G8_BAR;
;       G8_LDB(B0, 1, 0); G8_SCHED; G8_LDA(At, 1, 0); G8_STAGE(G8_SA(0, 1), a2 + hstepA, voffA);
;       G8_WAIT_L(8); G8_BAR; G8_WAIT_L(0); G8_MMA(0, 0, At, B0); G8_BAR; G8_SCHED;
;       G8_LDB(B1, 1, 1); G8_STAGE(G8_SB(1, 0), b3, voffB);
;       G8_BAR; G8_WAIT_L(0); G8_MMA(0, 1, At, B1); G8_BAR;
;       G8_LDA(At, 1, 1); G8_STAGE(G8_SA(1, 0), a3, voffA);
;       G8_BAR; G8_WAIT_L(0); G8_MMA(1, 0, At, B0); G8_BAR; G8_SCHED;
;       G8_STAGE(G8_SB(1, 1), b3 + hstepB, voffB);
;       G8_WAIT_V(6); G8_BAR; G8_MMA(1, 1, At, B1); G8_BAR;
;     }
;     E(acc, cur, wr, wc, fr, fq);
;     if (!has_next) break;
; #pragma unroll
;     for (int a = 0; a < 2; ++a)
; #pragma unroll
;       for (int b = 0; b < 2; ++b)
; #pragma unroll
;         for (int m = 0; m < 4; ++m)
; #pragma unroll
;           for (int n = 0; n < 2; ++n) acc[a][b][m][n] = (f32x4v){0.f, 0.f, 0.f, 0.f};
;     cur = nxt; cA = nA; cB = nB; ++ui;
.LBB0_429:
	s_add_i32 s48, s48, 1
	s_mov_b64 s[34:35], s[16:17]
	s_mul_i32 s16, s48, s95
	s_add_i32 s16, s16, s20
	s_cmpk_lt_u32 s16, 0xc0
	s_cselect_b64 s[38:39], -1, 0
	s_cmpk_gt_u32 s16, 0xbf
	s_cselect_b64 s[30:31], -1, 0
	s_lshr_b32 s17, s16, 2
	s_mov_b64 s[2:3], s[28:29]
	s_mov_b32 s1, s50
	s_mov_b32 s28, s49
	s_mov_b32 s56, s50
	s_mov_b32 s51, s49
	s_add_i32 s50, s17, s46
	s_and_b32 s49, s16, 3
	s_and_b64 s[16:17], s[38:39], exec
	s_cselect_b32 s16, s49, s28
	s_cselect_b32 s28, s50, s1
	s_ashr_i32 s29, s28, 31
	s_lshl_b64 s[28:29], s[28:29], 19
	s_add_u32 s28, s90, s28
	s_addc_u32 s29, s91, s29
	s_and_b64 s[58:59], s[38:39], exec
	s_cselect_b32 s57, s29, s3
	s_cselect_b32 s58, s28, s2
	s_ashr_i32 s17, s16, 31
	s_lshl_b64 s[16:17], s[16:17], 19
	s_add_u32 s16, s6, s16
	s_addc_u32 s17, s7, s17
	s_and_b64 s[38:39], s[38:39], exec
	s_cselect_b32 s59, s17, s35
	s_cselect_b32 s60, s16, s34
	s_add_u32 s2, s2, 0x40080
	s_addc_u32 s3, s3, 0
	s_add_u32 s61, s34, 0x100
	v_mov_b32_e32 v0, 0
	s_addc_u32 s62, s35, 0
	s_mov_b32 s63, -2
	s_waitcnt lgkmcnt(0)
	v_mov_b32_e32 v1, v0
	v_mov_b64_e32 v[2:3], v[0:1]
	v_mov_b64_e32 v[4:5], v[0:1]
	v_mov_b64_e32 v[6:7], v[0:1]
	v_mov_b64_e32 v[8:9], v[0:1]
	v_mov_b64_e32 v[10:11], v[0:1]
	v_mov_b64_e32 v[12:13], v[0:1]
	v_mov_b64_e32 v[14:15], v[0:1]
	v_mov_b64_e32 v[16:17], v[0:1]
	v_mov_b64_e32 v[18:19], v[0:1]
	v_mov_b64_e32 v[20:21], v[0:1]
	v_mov_b64_e32 v[22:23], v[0:1]
	v_mov_b64_e32 v[24:25], v[0:1]
	v_mov_b64_e32 v[26:27], v[0:1]
	v_mov_b64_e32 v[28:29], v[0:1]
	v_mov_b64_e32 v[30:31], v[0:1]
	v_mov_b64_e32 v[32:33], v[0:1]
	v_mov_b64_e32 v[34:35], v[0:1]
	v_mov_b64_e32 v[36:37], v[0:1]
	v_mov_b64_e32 v[38:39], v[0:1]
	v_mov_b64_e32 v[40:41], v[0:1]
	v_mov_b64_e32 v[42:43], v[0:1]
	v_mov_b64_e32 v[44:45], v[0:1]
	v_mov_b64_e32 v[46:47], v[0:1]
	v_mov_b64_e32 v[48:49], v[0:1]
	v_mov_b64_e32 v[50:51], v[0:1]
	v_mov_b64_e32 v[52:53], v[0:1]
	v_mov_b64_e32 v[54:55], v[0:1]
	v_mov_b64_e32 v[56:57], v[0:1]
	v_mov_b64_e32 v[58:59], v[0:1]
	v_mov_b64_e32 v[60:61], v[0:1]
	v_mov_b64_e32 v[62:63], v[0:1]
	v_mov_b64_e32 v[64:65], v[0:1]
	v_mov_b64_e32 v[66:67], v[0:1]
	v_mov_b64_e32 v[68:69], v[0:1]
	v_mov_b64_e32 v[70:71], v[0:1]
	v_mov_b64_e32 v[72:73], v[0:1]
	v_mov_b64_e32 v[74:75], v[0:1]
	v_mov_b64_e32 v[76:77], v[0:1]
	v_mov_b64_e32 v[78:79], v[0:1]
	v_mov_b64_e32 v[80:81], v[0:1]
	v_mov_b64_e32 v[82:83], v[0:1]
	v_mov_b64_e32 v[84:85], v[0:1]
	v_mov_b64_e32 v[86:87], v[0:1]
	v_mov_b64_e32 v[88:89], v[0:1]
	v_mov_b64_e32 v[90:91], v[0:1]
	v_mov_b64_e32 v[92:93], v[0:1]
	v_mov_b64_e32 v[94:95], v[0:1]
	v_mov_b64_e32 v[96:97], v[0:1]
	v_mov_b64_e32 v[98:99], v[0:1]
	v_mov_b64_e32 v[100:101], v[0:1]
	v_mov_b64_e32 v[102:103], v[0:1]
	v_mov_b64_e32 v[104:105], v[0:1]
	v_mov_b64_e32 v[106:107], v[0:1]
	v_mov_b64_e32 v[108:109], v[0:1]
	v_mov_b64_e32 v[110:111], v[0:1]
	v_mov_b64_e32 v[112:113], v[0:1]
	v_mov_b64_e32 v[114:115], v[0:1]
	v_mov_b64_e32 v[116:117], v[0:1]
	v_mov_b64_e32 v[118:119], v[0:1]
	v_mov_b64_e32 v[120:121], v[0:1]
	v_mov_b64_e32 v[122:123], v[0:1]
	v_mov_b64_e32 v[124:125], v[0:1]
	v_mov_b64_e32 v[126:127], v[0:1]

;   DI bool next(int k, Unit& u) const {
;     const int g = blockIdx.x & 7, j = blockIdx.x >> 3, J = gridDim.x >> 3;
;     const int q = k * J + j;
;     if (q >= R * NT) return false;
; template <class Epi>
; DI void gemm_phase(LAS unsigned char* lds, const u16* __restrict__ Aptr, int lda, const u16* __restrict__ Btptr, int K, const Order& S, const Epi& E) {
;     ...
;     const bool has_next = S.next(ui + 1, nxt);
;     const char* nA = has_next ? (const char*)Aptr + (size_t)nxt.pm * tstepA : cA;
;     const char* nB = has_next ? (const char*)Btptr + (size_t)nxt.pn * tstepB : cB;
;     for (int t = 0; t < nt; t += 2) {
;       const bool last = (t == nt - 2);
;       const char* a1 = cA + (size_t)(t + 1) * kstep;
;       const char* a2 = last ? nA : cA + (size_t)(t + 2) * kstep;
;       const char* b2 = last ? nB : cB + (size_t)(t + 2) * kstep;
;       const char* a3 = a2 + kstep;
;       const char* b3 = b2 + kstep;
;       G8_LDB(B0, 0, 0); G8_SCHED; G8_LDA(At, 0, 0); G8_STAGE(G8_SA(1, 1), a1 + hstepA, voffA);
;       G8_WAIT_L(8); G8_BAR; G8_WAIT_L(0); G8_MMA(0, 0, At, B0); G8_BAR; G8_SCHED;
;       G8_LDB(B1, 0, 1); G8_STAGE(G8_SB(0, 0), b2, voffB);
;       G8_BAR; G8_WAIT_L(0); G8_MMA(0, 1, At, B1); G8_BAR;
;       G8_LDA(At, 0, 1); G8_STAGE(G8_SA(0, 0), a2, voffA);
;       G8_BAR; G8_WAIT_L(0); G8_MMA(1, 0, At, B0); G8_BAR; G8_SCHED;
;       G8_STAGE(G8_SB(0, 1), b2 + hstepB, voffB);
;       G8_WAIT_V(6); G8_BAR; G8_MMA(1, 1, At, B1); G8_BAR;
;       G8_LDB(B0, 1, 0); G8_SCHED; G8_LDA(At, 1, 0); G8_STAGE(G8_SA(0, 1), a2 + hstepA, voffA);
;       G8_WAIT_L(8); G8_BAR; G8_WAIT_L(0); G8_MMA(0, 0, At, B0); G8_BAR; G8_SCHED;
;       G8_LDB(B1, 1, 1); G8_STAGE(G8_SB(1, 0), b3, voffB);
;       G8_BAR; G8_WAIT_L(0); G8_MMA(0, 1, At, B1); G8_BAR;
;       G8_LDA(At, 1, 1); G8_STAGE(G8_SA(1, 0), a3, voffA);
;       G8_BAR; G8_WAIT_L(0); G8_MMA(1, 0, At, B0); G8_BAR; G8_SCHED;
;       G8_STAGE(G8_SB(1, 1), b3 + hstepB, voffB);
;       G8_WAIT_V(6); G8_BAR; G8_MMA(1, 1, At, B1); G8_BAR;
;     }
;     E(acc, cur, wr, wc, fr, fq);
;     if (!has_next) break;
; #pragma unroll
;     for (int a = 0; a < 2; ++a)
; #pragma unroll
;       for (int b = 0; b < 2; ++b)
; #pragma unroll
;         for (int m = 0; m < 4; ++m)
; #pragma unroll
;           for (int n = 0; n < 2; ++n) acc[a][b][m][n] = (f32x4v){0.f, 0.f, 0.f, 0.f};
;     cur = nxt; cA = nA; cB = nB; ++ui;
.LBB0_455:
	s_add_i32 s49, s49, 1
	s_mul_i32 s7, s49, s95
	s_add_i32 s7, s7, s20
	s_cmpk_lt_u32 s7, 0xc0
	s_cselect_b64 s[36:37], -1, 0
	s_cmpk_gt_u32 s7, 0xbf
	s_mov_b64 s[34:35], s[16:17]
	s_cselect_b64 s[30:31], -1, 0
	s_lshr_b32 s16, s7, 2
	s_mov_b32 s5, s50
	s_mov_b32 s57, s51
	s_mov_b32 s56, s50
	s_add_i32 s51, s16, s46
	s_and_b32 s50, s7, 3
	s_and_b64 s[16:17], s[36:37], exec
	s_cselect_b32 s16, s50, s5
	s_mul_i32 s5, s51, 0xdc000
	v_readlane_b32 s7, v244, 3
	s_mov_b64 s[2:3], s[28:29]
	s_add_u32 s28, s7, s5
	v_readlane_b32 s5, v244, 4
	s_addc_u32 s29, s5, 0
	s_and_b64 s[38:39], s[36:37], exec
	s_cselect_b32 s58, s29, s3
	s_cselect_b32 s59, s28, s2
	s_ashr_i32 s17, s16, 31
	s_lshl_b64 s[16:17], s[16:17], 17
	s_add_u32 s16, s8, s16
	s_addc_u32 s17, s9, s17
	s_and_b64 s[36:37], s[36:37], exec
	v_mov_b32_e32 v0, 0
	s_cselect_b32 s60, s17, s35
	s_cselect_b32 s61, s16, s34
	s_mov_b64 s[36:37], -1
	s_mov_b64 s[38:39], 0
	s_mov_b32 s40, 0
	v_mov_b32_e32 v1, v0
	v_mov_b64_e32 v[2:3], v[0:1]
	v_mov_b64_e32 v[4:5], v[0:1]
	v_mov_b64_e32 v[6:7], v[0:1]
	v_mov_b64_e32 v[8:9], v[0:1]
	v_mov_b64_e32 v[10:11], v[0:1]
	v_mov_b64_e32 v[12:13], v[0:1]
	v_mov_b64_e32 v[14:15], v[0:1]
	v_mov_b64_e32 v[16:17], v[0:1]
	v_mov_b64_e32 v[18:19], v[0:1]
	v_mov_b64_e32 v[20:21], v[0:1]
	v_mov_b64_e32 v[22:23], v[0:1]
	v_mov_b64_e32 v[24:25], v[0:1]
	v_mov_b64_e32 v[26:27], v[0:1]
	v_mov_b64_e32 v[28:29], v[0:1]
	v_mov_b64_e32 v[30:31], v[0:1]
	v_mov_b64_e32 v[32:33], v[0:1]
	v_mov_b64_e32 v[34:35], v[0:1]
	v_mov_b64_e32 v[36:37], v[0:1]
	v_mov_b64_e32 v[38:39], v[0:1]
	v_mov_b64_e32 v[40:41], v[0:1]
	v_mov_b64_e32 v[42:43], v[0:1]
	v_mov_b64_e32 v[44:45], v[0:1]
	v_mov_b64_e32 v[46:47], v[0:1]
	v_mov_b64_e32 v[48:49], v[0:1]
	v_mov_b64_e32 v[50:51], v[0:1]
	v_mov_b64_e32 v[52:53], v[0:1]
	v_mov_b64_e32 v[54:55], v[0:1]
	v_mov_b64_e32 v[56:57], v[0:1]
	v_mov_b64_e32 v[58:59], v[0:1]
	v_mov_b64_e32 v[60:61], v[0:1]
	v_mov_b64_e32 v[62:63], v[0:1]
	v_mov_b64_e32 v[64:65], v[0:1]
	v_mov_b64_e32 v[66:67], v[0:1]
	v_mov_b64_e32 v[68:69], v[0:1]
	v_mov_b64_e32 v[70:71], v[0:1]
	v_mov_b64_e32 v[72:73], v[0:1]
	v_mov_b64_e32 v[74:75], v[0:1]
	v_mov_b64_e32 v[76:77], v[0:1]
	v_mov_b64_e32 v[78:79], v[0:1]
	v_mov_b64_e32 v[80:81], v[0:1]
	v_mov_b64_e32 v[82:83], v[0:1]
	v_mov_b64_e32 v[84:85], v[0:1]
	v_mov_b64_e32 v[86:87], v[0:1]
	v_mov_b64_e32 v[88:89], v[0:1]
	v_mov_b64_e32 v[90:91], v[0:1]
	v_mov_b64_e32 v[92:93], v[0:1]
	v_mov_b64_e32 v[94:95], v[0:1]
	v_mov_b64_e32 v[96:97], v[0:1]
	v_mov_b64_e32 v[98:99], v[0:1]
	v_mov_b64_e32 v[100:101], v[0:1]
	v_mov_b64_e32 v[102:103], v[0:1]
	v_mov_b64_e32 v[104:105], v[0:1]
	v_mov_b64_e32 v[106:107], v[0:1]
	v_mov_b64_e32 v[108:109], v[0:1]
	v_mov_b64_e32 v[110:111], v[0:1]
	v_mov_b64_e32 v[112:113], v[0:1]
	v_mov_b64_e32 v[114:115], v[0:1]
	v_mov_b64_e32 v[116:117], v[0:1]
	v_mov_b64_e32 v[118:119], v[0:1]
	v_mov_b64_e32 v[120:121], v[0:1]
	v_mov_b64_e32 v[122:123], v[0:1]
	v_mov_b64_e32 v[124:125], v[0:1]
	v_mov_b64_e32 v[126:127], v[0:1]
